# GQA attention loop with LDS-DMA staging: second barrier per tile removed (visibility via vmcnt(0) before barrier 1); on top of v41
# baseline (speedup 1.0000x reference)
; __device__ __forceinline__ void finishSM(f32x16& p0, f32x16& p1, float alpha, float& l_reg, bf16x8& pa0, bf16x8& pa1, bf16x8& pa2, bf16x8& pa3) {
; #pragma unroll
;   for (int r = 0; r < 16; ++r) p1[r] = __builtin_amdgcn_exp2f(p1[r]);
;   float ps = 0;
; #pragma unroll
;   for (int r = 0; r < 16; ++r) ps += p0[r];
; #pragma unroll
;   for (int r = 0; r < 16; ++r) ps += p1[r];
;   { auto rr = __builtin_amdgcn_permlane32_swap(__float_as_uint(ps), __float_as_uint(ps), false, false);
;     ps = __uint_as_float(rr[0]) + __uint_as_float(rr[1]); }
;   l_reg = l_reg * alpha + ps;
;     ...
;   PK4(p0, 0, pa0); PK4(p0, 8, pa1); PK4(p1, 0, pa2); PK4(p1, 8, pa3);
;     ...
; }
; template <int DK, int NPARK>
; __device__ __forceinline__ void qkt(f32x16& p0, f32x16& p1, const char* Ks, const bf16x8* qr, const char* qpark, int r32, int hi) {
;   p0 = f32x16{}; p1 = f32x16{};
; #pragma unroll
;   for (int d0 = 0; d0 < DK / 16; ++d0) { const int cb = (d0 * 16 + hi * 8) * 2;
;     bf16x8 b0 = *reinterpret_cast<const bf16x8*>(Ks + kswz<DK>(r32, cb));
;     bf16x8 b1 = *reinterpret_cast<const bf16x8*>(Ks + kswz<DK>(32 + r32, cb));
;     bf16x8 q;
;     if constexpr (NPARK > 0) { if (d0 >= DK / 16 - NPARK) q = *reinterpret_cast<const bf16x8*>(qpark + (d0 - (DK / 16 - NPARK)) * 1024); else q = qr[d0]; } else q = qr[d0];
;     p0 = __builtin_amdgcn_mfma_f32_32x32x16_bf16(b0, q, p0, 0, 0, 0);
;     p1 = __builtin_amdgcn_mfma_f32_32x32x16_bf16(b1, q, p1, 0, 0, 0); }
; }
.LBB0_924:
	s_add_u32 s48, s10, s67
	s_addc_u32 s49, s11, 0
	s_add_u32 m0, s52, 0x8000
	s_nop 0
	global_load_lds_dwordx4 v246, s[48:49]
	s_add_u32 m0, s52, 0x8400
	s_nop 0
	global_load_lds_dwordx4 v247, s[48:49]
	ds_read_b128 v[64:67], v161 offset:49152
	ds_read_b128 v[68:71], v161 offset:57344
	ds_read_b128 v[194:197], v170 offset:49152
	ds_read_b128 v[198:201], v170 offset:57344
	v_add_f32_e32 v144, v187, v145
	s_waitcnt lgkmcnt(3)
	v_mfma_f32_32x32x16_bf16 v[80:95], v[64:67], v[112:115], 0
	v_add_f32_e32 v144, v146, v144
	v_add_f32_e32 v144, v188, v144
	v_add_f32_e32 v144, v186, v144
	v_add_f32_e32 v144, v189, v144
	v_add_f32_e32 v144, v147, v144
	v_add_f32_e32 v144, v185, v144
	v_add_f32_e32 v144, v157, v144
	s_waitcnt lgkmcnt(2)
	v_mfma_f32_32x32x16_bf16 v[64:79], v[68:71], v[112:115], 0
	v_add_f32_e32 v144, v181, v144
	v_add_f32_e32 v144, v179, v144
	v_add_f32_e32 v144, v182, v144
	v_exp_f32_e32 v142, v142
	v_add_f32_e32 v144, v154, v144
	v_exp_f32_e32 v143, v143
	v_add_f32_e32 v144, v155, v144
	s_waitcnt lgkmcnt(1)
	v_mfma_f32_32x32x16_bf16 v[80:95], v[194:197], v[108:111], v[80:95]
	v_exp_f32_e32 v140, v140
	v_add_f32_e32 v144, v156, v144
	v_exp_f32_e32 v141, v141
	v_add_f32_e32 v144, v180, v144
	v_exp_f32_e32 v136, v136
	v_add_f32_e32 v144, v142, v144
	v_exp_f32_e32 v137, v137
	s_waitcnt lgkmcnt(0)
	v_mfma_f32_32x32x16_bf16 v[64:79], v[198:201], v[108:111], v[64:79]
	ds_read_b128 v[194:197], v169 offset:49152
	ds_read_b128 v[198:201], v169 offset:57344
	v_add_f32_e32 v144, v143, v144
	v_exp_f32_e32 v132, v132
	v_add_f32_e32 v144, v140, v144
	v_exp_f32_e32 v133, v133
	v_add_f32_e32 v144, v141, v144
	v_exp_f32_e32 v130, v130
	s_waitcnt lgkmcnt(1)
	v_mfma_f32_32x32x16_bf16 v[80:95], v[194:197], v[120:123], v[80:95]
	v_add_f32_e32 v144, v136, v144
	v_exp_f32_e32 v131, v131
	v_add_f32_e32 v144, v137, v144
	v_exp_f32_e32 v138, v138
	v_add_f32_e32 v144, v132, v144
	v_exp_f32_e32 v139, v139
	v_add_f32_e32 v144, v133, v144
	s_waitcnt lgkmcnt(0)
	v_mfma_f32_32x32x16_bf16 v[64:79], v[198:201], v[120:123], v[64:79]
	ds_read_b128 v[194:197], v168 offset:49152
	ds_read_b128 v[198:201], v168 offset:57344
	v_exp_f32_e32 v134, v134
	v_add_f32_e32 v144, v130, v144
	v_exp_f32_e32 v135, v135
	v_add_f32_e32 v144, v131, v144
	v_exp_f32_e32 v128, v128
	v_add_f32_e32 v144, v138, v144
	s_waitcnt lgkmcnt(1)
	v_mfma_f32_32x32x16_bf16 v[80:95], v[194:197], v[124:127], v[80:95]
	v_exp_f32_e32 v129, v129
	v_add_f32_e32 v144, v139, v144
	v_add_f32_e32 v144, v134, v144
	v_add_f32_e32 v144, v135, v144
	v_add_f32_e32 v144, v128, v144
	v_add_f32_e32 v175, v129, v144
	v_mov_b32_e32 v176, v175
	s_waitcnt lgkmcnt(0)
	v_mfma_f32_32x32x16_bf16 v[64:79], v[198:201], v[124:127], v[64:79]
	ds_read_b128 v[194:197], v167 offset:49152
	ds_read_b128 v[198:201], v167 offset:57344
	v_permlane32_swap_b32_e32 v175, v176
	s_waitcnt lgkmcnt(1)
	v_mfma_f32_32x32x16_bf16 v[80:95], v[194:197], v[116:119], v[80:95]
	s_waitcnt lgkmcnt(0)
	v_mfma_f32_32x32x16_bf16 v[64:79], v[198:201], v[116:119], v[64:79]
	ds_read_b128 v[194:197], v166 offset:49152
	ds_read_b128 v[198:201], v166 offset:57344
	s_waitcnt lgkmcnt(1)
	v_mfma_f32_32x32x16_bf16 v[80:95], v[194:197], v[104:107], v[80:95]
	s_waitcnt lgkmcnt(0)
	v_mfma_f32_32x32x16_bf16 v[64:79], v[198:201], v[104:107], v[64:79]
	ds_read_b128 v[194:197], v172 offset:49152
	ds_read_b128 v[198:201], v172 offset:57344
	s_waitcnt lgkmcnt(1)
	v_mfma_f32_32x32x16_bf16 v[80:95], v[194:197], v[100:103], v[80:95]
	s_waitcnt lgkmcnt(0)
	v_mfma_f32_32x32x16_bf16 v[64:79], v[198:201], v[100:103], v[64:79]
	ds_read_b128 v[194:197], v171 offset:49152
	ds_read_b128 v[198:201], v171 offset:57344
	v_cvt_pk_bf16_f32 v144, v145, v187
	v_cvt_pk_bf16_f32 v145, v146, v188
	v_cvt_pk_bf16_f32 v146, v186, v189
	v_cvt_pk_bf16_f32 v147, v147, v185
	v_cvt_pk_bf16_f32 v184, v157, v181
	v_cvt_pk_bf16_f32 v185, v179, v182
	s_waitcnt lgkmcnt(1)
	v_mfma_f32_32x32x16_bf16 v[80:95], v[194:197], v[96:99], v[80:95]
	v_permlane32_swap_b32_e32 v144, v146
	v_cvt_pk_bf16_f32 v186, v154, v155
	v_cvt_pk_bf16_f32 v187, v156, v180
	v_cvt_pk_bf16_f32 v180, v142, v143
	v_cvt_pk_bf16_f32 v181, v140, v141
	v_cvt_pk_bf16_f32 v182, v136, v137
	s_waitcnt lgkmcnt(0)
	v_mfma_f32_32x32x16_bf16 v[64:79], v[198:201], v[96:99], v[64:79]
	v_cvt_pk_bf16_f32 v183, v132, v133
	v_cvt_pk_bf16_f32 v188, v130, v131
	v_cvt_pk_bf16_f32 v189, v138, v139
	v_cvt_pk_bf16_f32 v190, v134, v135
	v_cvt_pk_bf16_f32 v191, v128, v129
	v_permlane32_swap_b32_e32 v145, v147
	v_permlane32_swap_b32_e32 v184, v186
	v_permlane32_swap_b32_e32 v185, v187
	v_permlane32_swap_b32_e32 v180, v182
	v_permlane32_swap_b32_e32 v181, v183
	v_permlane32_swap_b32_e32 v188, v190
	v_permlane32_swap_b32_e32 v189, v191
	ds_read_b64_tr_b16 v[194:195], v160 offset:0
	ds_read_b64_tr_b16 v[196:197], v160 offset:0x800
	ds_read_b64_tr_b16 v[198:199], v160 offset:0x1000
	ds_read_b64_tr_b16 v[200:201], v160 offset:0x1800
	ds_read_b64_tr_b16 v[202:203], v160 offset:0x2000
	ds_read_b64_tr_b16 v[204:205], v160 offset:0x2800
	ds_read_b64_tr_b16 v[206:207], v160 offset:0x3000
	ds_read_b64_tr_b16 v[208:209], v160 offset:0x3800
	s_waitcnt lgkmcnt(0)
	v_mfma_f32_32x32x16_bf16 v[0:15], v[144:147], v[194:197], v[0:15]
	ds_read_b64_tr_b16 v[194:195], v160 offset:0x200
	ds_read_b64_tr_b16 v[196:197], v160 offset:0xa00
	v_mfma_f32_32x32x16_bf16 v[0:15], v[184:187], v[198:201], v[0:15]
	ds_read_b64_tr_b16 v[198:199], v160 offset:0x1200
	ds_read_b64_tr_b16 v[200:201], v160 offset:0x1a00
	v_mfma_f32_32x32x16_bf16 v[0:15], v[180:183], v[202:205], v[0:15]
	ds_read_b64_tr_b16 v[202:203], v160 offset:0x2200
	ds_read_b64_tr_b16 v[204:205], v160 offset:0x2a00
	v_mfma_f32_32x32x16_bf16 v[0:15], v[188:191], v[206:209], v[0:15]
	ds_read_b64_tr_b16 v[206:207], v160 offset:0x3200
	ds_read_b64_tr_b16 v[208:209], v160 offset:0x3a00
	s_waitcnt lgkmcnt(0)
; #define SBAR() __builtin_amdgcn_sched_barrier(0)
; template <int DK>
; __device__ __forceinline__ void partialSM(f32x16& p0, f32x16& p1, float& m_reg, float& mn, float& alpha) {
;   constexpr float SCALE = Cst<DK>::SCALE, C = SCALE * 1.4426950408889634f;
;   float pmax = p0[0];
; #pragma unroll
;   for (int r = 1; r < 16; ++r) pmax = fmaxf(pmax, p0[r]);
; #pragma unroll
;   for (int r = 0; r < 16; ++r) pmax = fmaxf(pmax, p1[r]);
;   { auto rr = __builtin_amdgcn_permlane32_swap(__float_as_uint(pmax), __float_as_uint(pmax), false, false);
;     pmax = fmaxf(__uint_as_float(rr[0]), __uint_as_float(rr[1])); }
;   if (__builtin_expect(__all(pmax - m_reg <= THR / SCALE), 1)) { mn = m_reg; alpha = 1.f; }
;   else { mn = fmaxf(m_reg, pmax); alpha = __builtin_amdgcn_exp2f((m_reg - mn) * C); m_reg = mn; }
; template <int D0> __device__ __forceinline__ void pv_one(f32x16& od, int vb, bf16x8 pa0, bf16x8 pa1, bf16x8 pa2, bf16x8 pa3) {
;   const s16x4 l0 = tr_read<v_rd_off(D0, 0, 0)>(vb), h0 = tr_read<v_rd_off(D0, 0, 1)>(vb), l1 = tr_read<v_rd_off(D0, 1, 0)>(vb), h1 = tr_read<v_rd_off(D0, 1, 1)>(vb);
;   const s16x4 l2 = tr_read<v_rd_off(D0, 2, 0)>(vb), h2 = tr_read<v_rd_off(D0, 2, 1)>(vb), l3 = tr_read<v_rd_off(D0, 3, 0)>(vb), h3 = tr_read<v_rd_off(D0, 3, 1)>(vb);
;   asm volatile("s_waitcnt lgkmcnt(0)" ::: "memory"); SBAR();
;     ...
;   od = __builtin_amdgcn_mfma_f32_32x32x16_bf16(pa0, PK(l0, h0), od, 0, 0, 0);
;   od = __builtin_amdgcn_mfma_f32_32x32x16_bf16(pa1, PK(l1, h1), od, 0, 0, 0);
;   od = __builtin_amdgcn_mfma_f32_32x32x16_bf16(pa2, PK(l2, h2), od, 0, 0, 0);
;   od = __builtin_amdgcn_mfma_f32_32x32x16_bf16(pa3, PK(l3, h3), od, 0, 0, 0);
;     ...
; }
; __device__ __forceinline__ void pv_d0(f32x16* o, int vb, bf16x8 pa0, bf16x8 pa1, bf16x8 pa2, bf16x8 pa3) {
;   pv_one<0>(o[0], vb, pa0, pa1, pa2, pa3); pv_one<1>(o[1], vb, pa0, pa1, pa2, pa3); pv_one<2>(o[2], vb, pa0, pa1, pa2, pa3); pv_one<3>(o[3], vb, pa0, pa1, pa2, pa3);
	v_mfma_f32_32x32x16_bf16 v[48:63], v[144:147], v[194:197], v[48:63]
	ds_read_b64_tr_b16 v[194:195], v160 offset:0x400
	ds_read_b64_tr_b16 v[196:197], v160 offset:0xc00
	v_mfma_f32_32x32x16_bf16 v[48:63], v[184:187], v[198:201], v[48:63]
	ds_read_b64_tr_b16 v[198:199], v160 offset:0x1400
	ds_read_b64_tr_b16 v[200:201], v160 offset:0x1c00
	v_mfma_f32_32x32x16_bf16 v[48:63], v[180:183], v[202:205], v[48:63]
	ds_read_b64_tr_b16 v[202:203], v160 offset:0x2400
	ds_read_b64_tr_b16 v[204:205], v160 offset:0x2c00
	v_mfma_f32_32x32x16_bf16 v[48:63], v[188:191], v[206:209], v[48:63]
	ds_read_b64_tr_b16 v[206:207], v160 offset:0x3400
	ds_read_b64_tr_b16 v[208:209], v160 offset:0x3c00
	s_waitcnt lgkmcnt(0)
	v_mfma_f32_32x32x16_bf16 v[32:47], v[144:147], v[194:197], v[32:47]
	ds_read_b64_tr_b16 v[194:195], v160 offset:0x600
	ds_read_b64_tr_b16 v[196:197], v160 offset:0xe00
	v_mfma_f32_32x32x16_bf16 v[32:47], v[184:187], v[198:201], v[32:47]
	ds_read_b64_tr_b16 v[198:199], v160 offset:0x1600
	ds_read_b64_tr_b16 v[200:201], v160 offset:0x1e00
	v_mfma_f32_32x32x16_bf16 v[32:47], v[180:183], v[202:205], v[32:47]
	ds_read_b64_tr_b16 v[202:203], v160 offset:0x2600
	ds_read_b64_tr_b16 v[204:205], v160 offset:0x2e00
	v_mfma_f32_32x32x16_bf16 v[32:47], v[188:191], v[206:209], v[32:47]
	ds_read_b64_tr_b16 v[206:207], v160 offset:0x3600
	ds_read_b64_tr_b16 v[208:209], v160 offset:0x3e00
	s_waitcnt lgkmcnt(0)
	v_mfma_f32_32x32x16_bf16 v[16:31], v[144:147], v[194:197], v[16:31]
	v_max_f32_e32 v144, v80, v81
	v_max3_f32 v144, v144, v82, v83
	v_max3_f32 v144, v144, v84, v85
	v_max3_f32 v144, v144, v86, v87
	v_max3_f32 v144, v144, v88, v89
	v_max3_f32 v144, v144, v90, v91
	v_max3_f32 v144, v144, v92, v93
	v_mfma_f32_32x32x16_bf16 v[16:31], v[184:187], v[198:201], v[16:31]
	v_max3_f32 v144, v144, v94, v95
	v_max3_f32 v144, v144, v64, v65
	v_max3_f32 v144, v144, v66, v67
	v_max3_f32 v144, v144, v68, v69
	v_max3_f32 v144, v144, v70, v71
	v_max3_f32 v144, v144, v72, v73
	v_max3_f32 v144, v144, v74, v75
	v_max3_f32 v144, v144, v76, v77
	v_mfma_f32_32x32x16_bf16 v[16:31], v[180:183], v[202:205], v[16:31]
	v_max3_f32 v144, v144, v78, v79
	v_mov_b32_e32 v145, v144
	s_nop 1
	v_permlane32_swap_b32_e32 v144, v145
	v_max_f32_e32 v144, v144, v145
	v_sub_f32_e32 v145, v144, v174
	v_cmp_ge_f32_e32 vcc, s1, v145
	v_max_f32_e32 v144, v174, v144
	v_mfma_f32_32x32x16_bf16 v[16:31], v[188:191], v[206:209], v[16:31]
	v_sub_f32_e32 v145, v174, v144
	v_mul_f32_e32 v145, 0x3e0293ee, v145
	v_exp_f32_e32 v145, v145
	s_cmp_eq_u64 vcc, exec
	s_cselect_b64 s[8:9], -1, 0
	s_waitcnt vmcnt(0)
	s_barrier
	v_cndmask_b32_e64 v177, v145, 1.0, s[8:9]
	v_cmp_gt_f32_e32 vcc, 1.0, v177
	s_add_u32 s48, s10, s0
	s_addc_u32 s49, s11, 0
	s_mov_b32 m0, s52
	s_nop 0
	global_load_lds_dwordx4 v244, s[48:49]
	s_add_u32 m0, s52, 0x400
	s_nop 0
	global_load_lds_dwordx4 v245, s[48:49]
	s_cbranch_vccz .LBB0_928
	s_and_saveexec_b64 s[12:13], s[6:7]
	ds_write_b32 v151, v177 offset:128
	s_or_b64 exec, exec, s[12:13]
	s_waitcnt lgkmcnt(0)
	v_add_u32_e32 v140, s95, v150
	ds_read_b128 v[128:131], v140 offset:224
	ds_read_b128 v[132:135], v140 offset:192
	ds_read_b128 v[136:139], v140 offset:160
	ds_read_b128 v[140:143], v140 offset:128
	s_waitcnt lgkmcnt(3)
	v_pk_mul_f32 v[12:13], v[12:13], v[128:129]
	s_waitcnt lgkmcnt(2)
	v_pk_mul_f32 v[8:9], v[8:9], v[132:133]
	s_waitcnt lgkmcnt(1)
	v_pk_mul_f32 v[4:5], v[4:5], v[136:137]
	v_pk_mul_f32 v[14:15], v[14:15], v[130:131]
	v_pk_mul_f32 v[10:11], v[10:11], v[134:135]
	v_pk_mul_f32 v[6:7], v[6:7], v[138:139]
	s_waitcnt lgkmcnt(0)
	v_pk_mul_f32 v[2:3], v[2:3], v[142:143]
	v_pk_mul_f32 v[0:1], v[0:1], v[140:141]
	v_pk_mul_f32 v[60:61], v[60:61], v[128:129]
	v_pk_mul_f32 v[56:57], v[56:57], v[132:133]
	v_pk_mul_f32 v[52:53], v[52:53], v[136:137]
	v_pk_mul_f32 v[62:63], v[62:63], v[130:131]
	v_pk_mul_f32 v[58:59], v[58:59], v[134:135]
	v_pk_mul_f32 v[54:55], v[54:55], v[138:139]
	v_pk_mul_f32 v[50:51], v[50:51], v[142:143]
	v_pk_mul_f32 v[48:49], v[48:49], v[140:141]
	v_pk_mul_f32 v[44:45], v[44:45], v[128:129]
	v_pk_mul_f32 v[40:41], v[40:41], v[132:133]
	v_pk_mul_f32 v[36:37], v[36:37], v[136:137]
	v_pk_mul_f32 v[46:47], v[46:47], v[130:131]
	v_pk_mul_f32 v[42:43], v[42:43], v[134:135]
	v_pk_mul_f32 v[38:39], v[38:39], v[138:139]
	v_pk_mul_f32 v[34:35], v[34:35], v[142:143]
	v_pk_mul_f32 v[32:33], v[32:33], v[140:141]
	v_pk_mul_f32 v[28:29], v[28:29], v[128:129]
	v_pk_mul_f32 v[24:25], v[24:25], v[132:133]
	v_pk_mul_f32 v[20:21], v[20:21], v[136:137]
	v_pk_mul_f32 v[30:31], v[30:31], v[130:131]
	v_pk_mul_f32 v[26:27], v[26:27], v[134:135]
	v_pk_mul_f32 v[22:23], v[22:23], v[138:139]
	v_pk_mul_f32 v[18:19], v[18:19], v[142:143]
	v_pk_mul_f32 v[16:17], v[16:17], v[140:141]
; template <int DK>
; __device__ __forceinline__ void partialSM(f32x16& p0, f32x16& p1, float& m_reg, float& mn, float& alpha) {
;     ...
;   float mnC = -mn * C;
; #pragma unroll
;   for (int r = 0; r < 16; ++r) p0[r] = fmaf(p0[r], C, mnC);
; #pragma unroll
;   for (int r = 0; r < 16; ++r) p1[r] = fmaf(p1[r], C, mnC);
; #pragma unroll
;   for (int r = 0; r < 16; ++r) p0[r] = __builtin_amdgcn_exp2f(p0[r]);
; }
; template <int DK, int NPARK>
; __device__ __forceinline__ void qkt(f32x16& p0, f32x16& p1, const char* Ks, const bf16x8* qr, const char* qpark, int r32, int hi) {
;   p0 = f32x16{}; p1 = f32x16{};
; #pragma unroll
;   for (int d0 = 0; d0 < DK / 16; ++d0) { const int cb = (d0 * 16 + hi * 8) * 2;
;     bf16x8 b0 = *reinterpret_cast<const bf16x8*>(Ks + kswz<DK>(r32, cb));
;     bf16x8 b1 = *reinterpret_cast<const bf16x8*>(Ks + kswz<DK>(32 + r32, cb));
;     bf16x8 q;
;     if constexpr (NPARK > 0) { if (d0 >= DK / 16 - NPARK) q = *reinterpret_cast<const bf16x8*>(qpark + (d0 - (DK / 16 - NPARK)) * 1024); else q = qr[d0]; } else q = qr[d0];
;     p0 = __builtin_amdgcn_mfma_f32_32x32x16_bf16(b0, q, p0, 0, 0, 0);
;     p1 = __builtin_amdgcn_mfma_f32_32x32x16_bf16(b1, q, p1, 0, 0, 0); }
; }
.LBB0_928:
	v_cndmask_b32_e64 v174, v144, v174, s[8:9]
	v_mul_f32_e32 v144, 0xbe0293ee, v174
	v_pk_fma_f32 v[80:81], v[80:81], s[76:77], v[144:145] op_sel_hi:[1,0,0]
	v_pk_fma_f32 v[82:83], v[82:83], s[76:77], v[144:145] op_sel_hi:[1,0,0]
	v_pk_fma_f32 v[84:85], v[84:85], s[76:77], v[144:145] op_sel_hi:[1,0,0]
	v_pk_fma_f32 v[86:87], v[86:87], s[76:77], v[144:145] op_sel_hi:[1,0,0]
	v_pk_fma_f32 v[88:89], v[88:89], s[76:77], v[144:145] op_sel_hi:[1,0,0]
	v_pk_fma_f32 v[90:91], v[90:91], s[76:77], v[144:145] op_sel_hi:[1,0,0]
	v_pk_fma_f32 v[92:93], v[92:93], s[76:77], v[144:145] op_sel_hi:[1,0,0]
	v_pk_fma_f32 v[94:95], v[94:95], s[76:77], v[144:145] op_sel_hi:[1,0,0]
	v_fmamk_f32 v184, v64, 0x3e0293ee, v144
	v_fmamk_f32 v185, v65, 0x3e0293ee, v144
	v_fmamk_f32 v186, v66, 0x3e0293ee, v144
	v_fmamk_f32 v187, v67, 0x3e0293ee, v144
	v_fmamk_f32 v188, v68, 0x3e0293ee, v144
	v_fmamk_f32 v146, v69, 0x3e0293ee, v144
	v_fmamk_f32 v147, v70, 0x3e0293ee, v144
	v_fmamk_f32 v179, v71, 0x3e0293ee, v144
	v_fmamk_f32 v180, v72, 0x3e0293ee, v144
	v_fmamk_f32 v181, v73, 0x3e0293ee, v144
	v_fmamk_f32 v182, v74, 0x3e0293ee, v144
	v_fmamk_f32 v183, v75, 0x3e0293ee, v144
	v_fmamk_f32 v145, v76, 0x3e0293ee, v144
	v_fmamk_f32 v189, v77, 0x3e0293ee, v144
	v_fmamk_f32 v190, v78, 0x3e0293ee, v144
	v_fmac_f32_e32 v144, 0x3e0293ee, v79
	v_exp_f32_e32 v141, v80
	v_exp_f32_e32 v143, v81
	v_exp_f32_e32 v139, v82
	v_exp_f32_e32 v142, v83
	v_exp_f32_e32 v138, v84
	v_exp_f32_e32 v140, v85
	v_exp_f32_e32 v136, v86
	v_exp_f32_e32 v137, v87
	v_exp_f32_e32 v133, v88
	v_exp_f32_e32 v135, v89
	v_exp_f32_e32 v132, v90
	v_exp_f32_e32 v134, v91
	v_exp_f32_e32 v129, v92
	v_exp_f32_e32 v131, v93
	v_exp_f32_e32 v128, v94
	v_exp_f32_e32 v130, v95
	s_waitcnt lgkmcnt(0)
	s_add_u32 s48, s10, s64
	s_addc_u32 s49, s11, 0
	s_add_u32 m0, s52, 0xc000
	s_nop 0
	global_load_lds_dwordx4 v246, s[48:49]
	s_add_u32 m0, s52, 0xc400
	s_nop 0
	global_load_lds_dwordx4 v247, s[48:49]
	ds_read_b128 v[64:67], v161 offset:32768
	ds_read_b128 v[68:71], v161 offset:40960
	ds_read_b128 v[194:197], v170 offset:32768
	ds_read_b128 v[198:201], v170 offset:40960
	v_exp_f32_e32 v203, v144
	s_waitcnt lgkmcnt(3)
	v_mfma_f32_32x32x16_bf16 v[80:95], v[64:67], v[112:115], 0
	v_add_f32_e32 v144, v143, v141
	v_add_f32_e32 v144, v139, v144
	v_add_f32_e32 v144, v142, v144
	v_add_f32_e32 v144, v138, v144
	v_add_f32_e32 v144, v140, v144
	v_add_f32_e32 v144, v136, v144
	v_add_f32_e32 v144, v137, v144
	s_waitcnt lgkmcnt(2)
	v_mfma_f32_32x32x16_bf16 v[64:79], v[68:71], v[112:115], 0
	v_add_f32_e32 v144, v133, v144
	v_add_f32_e32 v144, v135, v144
	v_add_f32_e32 v144, v132, v144
	v_add_f32_e32 v144, v134, v144
	v_exp_f32_e32 v191, v184
	v_add_f32_e32 v144, v129, v144
	v_exp_f32_e32 v185, v185
	s_waitcnt lgkmcnt(1)
	v_mfma_f32_32x32x16_bf16 v[80:95], v[194:197], v[108:111], v[80:95]
	v_add_f32_e32 v144, v131, v144
	v_add_f32_e32 v144, v128, v144
	v_add_f32_e32 v144, v130, v144
	v_add_f32_e32 v144, v191, v144
	v_add_f32_e32 v144, v185, v144
	v_exp_f32_e32 v179, v179
	v_exp_f32_e32 v180, v180
	s_waitcnt lgkmcnt(0)
	v_mfma_f32_32x32x16_bf16 v[64:79], v[198:201], v[108:111], v[64:79]
	ds_read_b128 v[194:197], v169 offset:32768
	ds_read_b128 v[198:201], v169 offset:40960
	v_exp_f32_e32 v181, v181
	v_exp_f32_e32 v182, v182
	v_exp_f32_e32 v202, v189
	v_exp_f32_e32 v190, v190
	s_waitcnt lgkmcnt(1)
	v_mfma_f32_32x32x16_bf16 v[80:95], v[194:197], v[120:123], v[80:95]
	s_waitcnt lgkmcnt(0)
	v_mfma_f32_32x32x16_bf16 v[64:79], v[198:201], v[120:123], v[64:79]
	ds_read_b128 v[194:197], v168 offset:32768
	ds_read_b128 v[198:201], v168 offset:40960
	s_waitcnt lgkmcnt(1)
	v_mfma_f32_32x32x16_bf16 v[80:95], v[194:197], v[124:127], v[80:95]
	s_waitcnt lgkmcnt(0)
	v_mfma_f32_32x32x16_bf16 v[64:79], v[198:201], v[124:127], v[64:79]
	ds_read_b128 v[194:197], v167 offset:32768
	ds_read_b128 v[198:201], v167 offset:40960
	s_waitcnt lgkmcnt(1)
	v_mfma_f32_32x32x16_bf16 v[80:95], v[194:197], v[116:119], v[80:95]
	s_waitcnt lgkmcnt(0)
	v_mfma_f32_32x32x16_bf16 v[64:79], v[198:201], v[116:119], v[64:79]
	ds_read_b128 v[194:197], v166 offset:32768
	ds_read_b128 v[198:201], v166 offset:40960
	s_waitcnt lgkmcnt(1)
	v_mfma_f32_32x32x16_bf16 v[80:95], v[194:197], v[104:107], v[80:95]
	s_waitcnt lgkmcnt(0)
	v_mfma_f32_32x32x16_bf16 v[64:79], v[198:201], v[104:107], v[64:79]
	ds_read_b128 v[194:197], v172 offset:32768
	ds_read_b128 v[198:201], v172 offset:40960
	s_waitcnt lgkmcnt(1)
	v_mfma_f32_32x32x16_bf16 v[80:95], v[194:197], v[100:103], v[80:95]
	s_waitcnt lgkmcnt(0)
	v_mfma_f32_32x32x16_bf16 v[64:79], v[198:201], v[100:103], v[64:79]
	ds_read_b128 v[194:197], v171 offset:32768
	ds_read_b128 v[198:201], v171 offset:40960
	s_waitcnt lgkmcnt(1)
	v_mfma_f32_32x32x16_bf16 v[80:95], v[194:197], v[96:99], v[80:95]
	v_exp_f32_e32 v195, v186
	v_exp_f32_e32 v196, v187
	v_exp_f32_e32 v197, v188
	v_add_f32_e32 v144, v195, v144
	v_add_f32_e32 v144, v196, v144
	v_add_f32_e32 v144, v197, v144
	s_waitcnt lgkmcnt(0)
; __device__ __forceinline__ void finishSM(f32x16& p0, f32x16& p1, float alpha, float& l_reg, bf16x8& pa0, bf16x8& pa1, bf16x8& pa2, bf16x8& pa3) {
; #pragma unroll
;   for (int r = 0; r < 16; ++r) p1[r] = __builtin_amdgcn_exp2f(p1[r]);
;   float ps = 0;
; #pragma unroll
;   for (int r = 0; r < 16; ++r) ps += p0[r];
; #pragma unroll
;   for (int r = 0; r < 16; ++r) ps += p1[r];
;   { auto rr = __builtin_amdgcn_permlane32_swap(__float_as_uint(ps), __float_as_uint(ps), false, false);
;     ps = __uint_as_float(rr[0]) + __uint_as_float(rr[1]); }
;   l_reg = l_reg * alpha + ps;
;     ...
;   PK4(p0, 0, pa0); PK4(p0, 8, pa1); PK4(p1, 0, pa2); PK4(p1, 8, pa3);
;     ...
; }
; template <int DK, int NPARK>
; __device__ __forceinline__ void qkt(f32x16& p0, f32x16& p1, const char* Ks, const bf16x8* qr, const char* qpark, int r32, int hi) {
;   p0 = f32x16{}; p1 = f32x16{};
; #pragma unroll
;   for (int d0 = 0; d0 < DK / 16; ++d0) { const int cb = (d0 * 16 + hi * 8) * 2;
;     bf16x8 b0 = *reinterpret_cast<const bf16x8*>(Ks + kswz<DK>(r32, cb));
;     bf16x8 b1 = *reinterpret_cast<const bf16x8*>(Ks + kswz<DK>(32 + r32, cb));
;     bf16x8 q;
;     if constexpr (NPARK > 0) { if (d0 >= DK / 16 - NPARK) q = *reinterpret_cast<const bf16x8*>(qpark + (d0 - (DK / 16 - NPARK)) * 1024); else q = qr[d0]; } else q = qr[d0];
;     p0 = __builtin_amdgcn_mfma_f32_32x32x16_bf16(b0, q, p0, 0, 0, 0);
;     p1 = __builtin_amdgcn_mfma_f32_32x32x16_bf16(b1, q, p1, 0, 0, 0); }
; }
; __device__ __forceinline__ int v_st(int k, int c) { const int kk = (k & ~0xC) | ((k & 4) << 1) | ((k & 8) >> 1); return ((kk >> 3) * 4 + (c >> 5)) * 512 + ((kk & 7) * 32 + (c & 31)) * 2; }
; __device__ __forceinline__ int v_rd_base(int lane) { return ((lane & 3) << 3) | (((lane >> 2) & 3) << 6) | (((lane >> 4) & 1) << 5) | (((lane >> 5) & 1) << 8); }
; template <int OFF> __device__ __forceinline__ s16x4 tr_read(int vb) {
;   s16x4 r; asm volatile("ds_read_b64_tr_b16 %0, %1 offset:%2" : "=&v"(r) : "v"(vb), "i"(OFF) : "memory"); return r;
; }
; template <int D0> __device__ __forceinline__ void pv_one(f32x16& od, int vb, bf16x8 pa0, bf16x8 pa1, bf16x8 pa2, bf16x8 pa3) {
;   const s16x4 l0 = tr_read<v_rd_off(D0, 0, 0)>(vb), h0 = tr_read<v_rd_off(D0, 0, 1)>(vb), l1 = tr_read<v_rd_off(D0, 1, 0)>(vb), h1 = tr_read<v_rd_off(D0, 1, 1)>(vb);
	v_mfma_f32_32x32x16_bf16 v[64:79], v[198:201], v[96:99], v[64:79]
	v_exp_f32_e32 v198, v146
	v_exp_f32_e32 v199, v147
	v_exp_f32_e32 v200, v183
	v_exp_f32_e32 v201, v145
	v_add_f32_e32 v144, v198, v144
	v_add_f32_e32 v144, v199, v144
	v_add_f32_e32 v144, v179, v144
	v_add_f32_e32 v144, v180, v144
	v_add_f32_e32 v144, v181, v144
	v_add_f32_e32 v144, v182, v144
	v_add_f32_e32 v144, v200, v144
	v_add_f32_e32 v144, v201, v144
	v_add_f32_e32 v144, v202, v144
	v_add_f32_e32 v144, v190, v144
	v_add_f32_e32 v183, v203, v144
	v_mov_b32_e32 v184, v183
	v_cvt_pk_bf16_f32 v144, v141, v143
	v_cvt_pk_bf16_f32 v145, v139, v142
	v_cvt_pk_bf16_f32 v146, v138, v140
	v_cvt_pk_bf16_f32 v147, v136, v137
	s_nop 1
	v_permlane32_swap_b32_e32 v183, v184
	v_permlane32_swap_b32_e32 v144, v146
	v_permlane32_swap_b32_e32 v145, v147
	v_cvt_pk_bf16_f32 v186, v133, v135
	v_cvt_pk_bf16_f32 v187, v132, v134
	v_cvt_pk_bf16_f32 v188, v129, v131
	v_cvt_pk_bf16_f32 v189, v128, v130
	v_cvt_pk_bf16_f32 v194, v191, v185
	v_cvt_pk_bf16_f32 v195, v195, v196
	v_cvt_pk_bf16_f32 v196, v197, v198
	v_cvt_pk_bf16_f32 v197, v199, v179
	v_cvt_pk_bf16_f32 v198, v180, v181
	v_cvt_pk_bf16_f32 v199, v182, v200
	v_cvt_pk_bf16_f32 v200, v201, v202
	v_cvt_pk_bf16_f32 v201, v190, v203
	s_nop 0
	v_permlane32_swap_b32_e32 v186, v188
	v_permlane32_swap_b32_e32 v187, v189
	v_permlane32_swap_b32_e32 v194, v196
	v_permlane32_swap_b32_e32 v195, v197
	v_permlane32_swap_b32_e32 v198, v200
	v_permlane32_swap_b32_e32 v199, v201
	ds_read_b64_tr_b16 v[154:155], v159 offset:0
	ds_read_b64_tr_b16 v[156:157], v159 offset:0x800
	ds_read_b64_tr_b16 v[202:203], v159 offset:0x1000
	ds_read_b64_tr_b16 v[204:205], v159 offset:0x1800
	ds_read_b64_tr_b16 v[206:207], v159 offset:0x2000
	ds_read_b64_tr_b16 v[208:209], v159 offset:0x2800
	ds_read_b64_tr_b16 v[210:211], v159 offset:0x3000
	ds_read_b64_tr_b16 v[212:213], v159 offset:0x3800
	s_waitcnt lgkmcnt(0)
	v_mfma_f32_32x32x16_bf16 v[0:15], v[144:147], v[154:157], v[0:15]
	ds_read_b64_tr_b16 v[154:155], v159 offset:0x200
	ds_read_b64_tr_b16 v[156:157], v159 offset:0xa00
	v_mfma_f32_32x32x16_bf16 v[0:15], v[186:189], v[202:205], v[0:15]
	ds_read_b64_tr_b16 v[202:203], v159 offset:0x1200
	ds_read_b64_tr_b16 v[204:205], v159 offset:0x1a00
	v_mfma_f32_32x32x16_bf16 v[0:15], v[194:197], v[206:209], v[0:15]
	ds_read_b64_tr_b16 v[206:207], v159 offset:0x2200
	ds_read_b64_tr_b16 v[208:209], v159 offset:0x2a00
	v_mfma_f32_32x32x16_bf16 v[0:15], v[198:201], v[210:213], v[0:15]
	ds_read_b64_tr_b16 v[210:211], v159 offset:0x3200
	ds_read_b64_tr_b16 v[212:213], v159 offset:0x3a00
	s_waitcnt lgkmcnt(0)
	v_mfma_f32_32x32x16_bf16 v[48:63], v[144:147], v[154:157], v[48:63]
	ds_read_b64_tr_b16 v[154:155], v159 offset:0x400
	ds_read_b64_tr_b16 v[156:157], v159 offset:0xc00
	v_mfma_f32_32x32x16_bf16 v[48:63], v[186:189], v[202:205], v[48:63]
	ds_read_b64_tr_b16 v[202:203], v159 offset:0x1400
	ds_read_b64_tr_b16 v[204:205], v159 offset:0x1c00
	v_mfma_f32_32x32x16_bf16 v[48:63], v[194:197], v[206:209], v[48:63]
	ds_read_b64_tr_b16 v[206:207], v159 offset:0x2400
	ds_read_b64_tr_b16 v[208:209], v159 offset:0x2c00
	v_mfma_f32_32x32x16_bf16 v[48:63], v[198:201], v[210:213], v[48:63]
	ds_read_b64_tr_b16 v[210:211], v159 offset:0x3400
	ds_read_b64_tr_b16 v[212:213], v159 offset:0x3c00
	s_waitcnt lgkmcnt(0)
	v_mfma_f32_32x32x16_bf16 v[32:47], v[144:147], v[154:157], v[32:47]
	ds_read_b64_tr_b16 v[154:155], v159 offset:0x600
	ds_read_b64_tr_b16 v[156:157], v159 offset:0xe00
	v_mfma_f32_32x32x16_bf16 v[32:47], v[186:189], v[202:205], v[32:47]
	ds_read_b64_tr_b16 v[202:203], v159 offset:0x1600
	ds_read_b64_tr_b16 v[204:205], v159 offset:0x1e00
	v_mfma_f32_32x32x16_bf16 v[32:47], v[194:197], v[206:209], v[32:47]
	ds_read_b64_tr_b16 v[206:207], v159 offset:0x2600
	ds_read_b64_tr_b16 v[208:209], v159 offset:0x2e00
	v_mfma_f32_32x32x16_bf16 v[32:47], v[198:201], v[210:213], v[32:47]
	ds_read_b64_tr_b16 v[210:211], v159 offset:0x3600
	ds_read_b64_tr_b16 v[212:213], v159 offset:0x3e00
	s_waitcnt lgkmcnt(0)
	v_mfma_f32_32x32x16_bf16 v[16:31], v[144:147], v[154:157], v[16:31]
	v_max_f32_e32 v144, v80, v81
	v_max3_f32 v144, v144, v82, v83
	v_max3_f32 v144, v144, v84, v85
	v_max3_f32 v144, v144, v86, v87
	v_max3_f32 v144, v144, v88, v89
	v_max3_f32 v144, v144, v90, v91
	v_max3_f32 v144, v144, v92, v93
	v_mfma_f32_32x32x16_bf16 v[16:31], v[186:189], v[202:205], v[16:31]
	v_max3_f32 v144, v144, v94, v95
	v_max3_f32 v144, v144, v64, v65
	v_max3_f32 v144, v144, v66, v67
	v_max3_f32 v144, v144, v68, v69
	v_max3_f32 v144, v144, v70, v71
	v_max3_f32 v144, v144, v72, v73
	v_max3_f32 v144, v144, v74, v75
	v_max3_f32 v144, v144, v76, v77
	v_mfma_f32_32x32x16_bf16 v[16:31], v[194:197], v[206:209], v[16:31]
	v_max3_f32 v144, v144, v78, v79
	v_mov_b32_e32 v145, v144
	s_nop 1
	v_permlane32_swap_b32_e32 v144, v145
	v_max_f32_e32 v144, v144, v145
	v_sub_f32_e32 v145, v144, v174
	v_cmp_ge_f32_e32 vcc, s1, v145
	v_max_f32_e32 v145, v174, v144
	v_mfma_f32_32x32x16_bf16 v[16:31], v[198:201], v[210:213], v[16:31]
	v_sub_f32_e32 v144, v174, v145
	v_mul_f32_e32 v144, 0x3e0293ee, v144
	v_exp_f32_e32 v144, v144
	s_cmp_eq_u64 vcc, exec
	s_cselect_b64 s[8:9], -1, 0
	s_waitcnt vmcnt(0)
	s_barrier
; template <int DK>
; __device__ __forceinline__ void partialSM(f32x16& p0, f32x16& p1, float& m_reg, float& mn, float& alpha) {
;     ...
;   float mnC = -mn * C;
; #pragma unroll
;   for (int r = 0; r < 16; ++r) p0[r] = fmaf(p0[r], C, mnC);
; #pragma unroll
;   for (int r = 0; r < 16; ++r) p1[r] = fmaf(p1[r], C, mnC);
; #pragma unroll
;   for (int r = 0; r < 16; ++r) p0[r] = __builtin_amdgcn_exp2f(p0[r]);
; }
	v_cndmask_b32_e64 v144, v144, 1.0, s[8:9]
	v_cmp_gt_f32_e32 vcc, 1.0, v144
	s_add_u32 s48, s10, s61
	s_addc_u32 s49, s11, 0
	s_add_u32 m0, s52, 0x4000
	s_nop 0
	global_load_lds_dwordx4 v244, s[48:49]
	s_add_u32 m0, s52, 0x4400
	s_nop 0
	global_load_lds_dwordx4 v245, s[48:49]
	s_cbranch_vccz .LBB0_932
	s_and_saveexec_b64 s[12:13], s[6:7]
	ds_write_b32 v151, v144 offset:128
	s_or_b64 exec, exec, s[12:13]
	s_waitcnt lgkmcnt(0)
	v_add_u32_e32 v140, s95, v150
	ds_read_b128 v[128:131], v140 offset:224
	ds_read_b128 v[132:135], v140 offset:192
	ds_read_b128 v[136:139], v140 offset:160
	ds_read_b128 v[140:143], v140 offset:128
	s_waitcnt lgkmcnt(3)
	v_pk_mul_f32 v[12:13], v[12:13], v[128:129]
	s_waitcnt lgkmcnt(2)
	v_pk_mul_f32 v[8:9], v[8:9], v[132:133]
	s_waitcnt lgkmcnt(1)
	v_pk_mul_f32 v[4:5], v[4:5], v[136:137]
	v_pk_mul_f32 v[14:15], v[14:15], v[130:131]
	v_pk_mul_f32 v[10:11], v[10:11], v[134:135]
	v_pk_mul_f32 v[6:7], v[6:7], v[138:139]
	s_waitcnt lgkmcnt(0)
	v_pk_mul_f32 v[2:3], v[2:3], v[142:143]
	v_pk_mul_f32 v[0:1], v[0:1], v[140:141]
	v_pk_mul_f32 v[60:61], v[60:61], v[128:129]
	v_pk_mul_f32 v[56:57], v[56:57], v[132:133]
	v_pk_mul_f32 v[52:53], v[52:53], v[136:137]
	v_pk_mul_f32 v[62:63], v[62:63], v[130:131]
	v_pk_mul_f32 v[58:59], v[58:59], v[134:135]
	v_pk_mul_f32 v[54:55], v[54:55], v[138:139]
	v_pk_mul_f32 v[50:51], v[50:51], v[142:143]
	v_pk_mul_f32 v[48:49], v[48:49], v[140:141]
	v_pk_mul_f32 v[44:45], v[44:45], v[128:129]
	v_pk_mul_f32 v[40:41], v[40:41], v[132:133]
	v_pk_mul_f32 v[36:37], v[36:37], v[136:137]
	v_pk_mul_f32 v[46:47], v[46:47], v[130:131]
	v_pk_mul_f32 v[42:43], v[42:43], v[134:135]
	v_pk_mul_f32 v[38:39], v[38:39], v[138:139]
	v_pk_mul_f32 v[34:35], v[34:35], v[142:143]
	v_pk_mul_f32 v[32:33], v[32:33], v[140:141]
	v_pk_mul_f32 v[28:29], v[28:29], v[128:129]
	v_pk_mul_f32 v[24:25], v[24:25], v[132:133]
	v_pk_mul_f32 v[20:21], v[20:21], v[136:137]
	v_pk_mul_f32 v[30:31], v[30:31], v[130:131]
	v_pk_mul_f32 v[26:27], v[26:27], v[134:135]
	v_pk_mul_f32 v[22:23], v[22:23], v[138:139]
	v_pk_mul_f32 v[18:19], v[18:19], v[142:143]
	v_pk_mul_f32 v[16:17], v[16:17], v[140:141]
.LBB0_932:
	v_cndmask_b32_e64 v174, v145, v174, s[8:9]
	v_mul_f32_e32 v128, 0xbe0293ee, v174
	v_pk_fma_f32 v[80:81], v[80:81], s[76:77], v[128:129] op_sel_hi:[1,0,0]
	v_pk_fma_f32 v[82:83], v[82:83], s[76:77], v[128:129] op_sel_hi:[1,0,0]
	v_pk_fma_f32 v[84:85], v[84:85], s[76:77], v[128:129] op_sel_hi:[1,0,0]
	v_pk_fma_f32 v[86:87], v[86:87], s[76:77], v[128:129] op_sel_hi:[1,0,0]
	v_pk_fma_f32 v[88:89], v[88:89], s[76:77], v[128:129] op_sel_hi:[1,0,0]
	v_pk_fma_f32 v[90:91], v[90:91], s[76:77], v[128:129] op_sel_hi:[1,0,0]
	v_pk_fma_f32 v[92:93], v[92:93], s[76:77], v[128:129] op_sel_hi:[1,0,0]
	v_pk_fma_f32 v[94:95], v[94:95], s[76:77], v[128:129] op_sel_hi:[1,0,0]
	v_exp_f32_e32 v145, v80
	v_exp_f32_e32 v187, v81
	v_exp_f32_e32 v146, v82
	v_exp_f32_e32 v188, v83
	v_exp_f32_e32 v186, v84
	v_exp_f32_e32 v189, v85
	v_exp_f32_e32 v147, v86
	v_exp_f32_e32 v185, v87
	v_exp_f32_e32 v157, v88
	v_exp_f32_e32 v181, v89
	v_exp_f32_e32 v179, v90
	v_exp_f32_e32 v182, v91
	v_exp_f32_e32 v154, v92
	v_exp_f32_e32 v155, v93
	v_exp_f32_e32 v156, v94
	v_exp_f32_e32 v180, v95
	v_pk_fma_f32 v[142:143], v[64:65], s[76:77], v[128:129] op_sel_hi:[1,0,0]
	v_add_f32_e32 v64, v175, v176
	s_add_u32 s10, s10, 0x10000
	v_fmac_f32_e32 v64, v173, v158
	v_add_f32_e32 v158, v183, v184
	s_addc_u32 s11, s11, 0
	s_add_i32 s14, s14, 2
	v_pk_fma_f32 v[140:141], v[66:67], s[76:77], v[128:129] op_sel_hi:[1,0,0]
	v_pk_fma_f32 v[136:137], v[68:69], s[76:77], v[128:129] op_sel_hi:[1,0,0]
	v_pk_fma_f32 v[132:133], v[70:71], s[76:77], v[128:129] op_sel_hi:[1,0,0]
	v_pk_fma_f32 v[130:131], v[72:73], s[76:77], v[128:129] op_sel_hi:[1,0,0]
	v_pk_fma_f32 v[138:139], v[74:75], s[76:77], v[128:129] op_sel_hi:[1,0,0]
	v_pk_fma_f32 v[134:135], v[76:77], s[76:77], v[128:129] op_sel_hi:[1,0,0]
	v_pk_fma_f32 v[128:129], v[78:79], s[76:77], v[128:129] op_sel_hi:[1,0,0]
	v_fmac_f32_e32 v158, v64, v177
	s_cmp_ge_u32 s14, s43
	s_waitcnt lgkmcnt(0)
	s_cbranch_scc1 .LBB0_934
	v_mov_b32_e32 v173, v144
	s_branch .LBB0_924
